# first grid barrier: the 16 per-XCD census counter reads of a poll round issued back to back and summed after one wait
# baseline (speedup 1.0000x reference)
.LBB0_866:
	v_readlane_b32 s2, v251, 42
	v_readlane_b32 s3, v251, 43
	v_readlane_b32 s4, v249, 0
	s_nop 3
	global_load_dword v0, v1, s[2:3] sc1
	v_readlane_b32 s2, v251, 44
	v_readlane_b32 s3, v251, 45
	s_waitcnt lgkmcnt(0)
	s_nop 3
	global_load_dword v2, v1, s[2:3] sc1
	v_readlane_b32 s2, v251, 46
	v_readlane_b32 s3, v251, 47
	s_nop 1
	s_nop 2
	global_load_dword v3, v1, s[2:3] sc1
	v_readlane_b32 s2, v251, 48
	v_readlane_b32 s3, v251, 49
	s_nop 1
	s_nop 2
	global_load_dword v4, v1, s[2:3] sc1
	v_readlane_b32 s2, v251, 50
	v_readlane_b32 s3, v251, 51
	s_nop 1
	s_nop 2
	global_load_dword v5, v1, s[2:3] sc1
	v_readlane_b32 s2, v251, 52
	v_readlane_b32 s3, v251, 53
	s_nop 1
	s_nop 2
	global_load_dword v6, v1, s[2:3] sc1
	v_readlane_b32 s2, v251, 54
	v_readlane_b32 s3, v251, 55
	s_nop 1
	s_nop 2
	global_load_dword v7, v1, s[2:3] sc1
	v_readlane_b32 s2, v251, 56
	v_readlane_b32 s3, v251, 57
	s_nop 1
	s_nop 2
	global_load_dword v8, v1, s[2:3] sc1
	v_readlane_b32 s2, v251, 58
	v_readlane_b32 s3, v251, 59
	s_nop 1
	s_nop 2
	global_load_dword v9, v1, s[2:3] sc1
	v_readlane_b32 s2, v251, 60
	v_readlane_b32 s3, v251, 61
	s_nop 1
	s_nop 2
	global_load_dword v10, v1, s[2:3] sc1
	v_readlane_b32 s2, v251, 62
	v_readlane_b32 s3, v251, 63
	s_nop 1
	s_nop 2
	global_load_dword v11, v1, s[2:3] sc1
	v_readlane_b32 s2, v252, 0
	v_readlane_b32 s3, v252, 1
	s_nop 1
	s_nop 2
	global_load_dword v12, v1, s[2:3] sc1
	v_readlane_b32 s2, v252, 2
	v_readlane_b32 s3, v252, 3
	s_nop 1
	s_nop 2
	global_load_dword v13, v1, s[2:3] sc1
	v_readlane_b32 s2, v252, 4
	v_readlane_b32 s3, v252, 5
	s_nop 1
	s_nop 2
	global_load_dword v14, v1, s[2:3] sc1
	v_readlane_b32 s2, v252, 6
	v_readlane_b32 s3, v252, 7
	s_nop 1
	s_nop 2
	global_load_dword v15, v1, s[2:3] sc1
	v_readlane_b32 s2, v252, 8
	v_readlane_b32 s3, v252, 9
	s_nop 1
	s_nop 2
	global_load_dword v16, v1, s[2:3] sc1
	s_mov_b64 s[2:3], -1
	s_waitcnt vmcnt(0)
	v_add_u32_e32 v17, v2, v0
	v_add_u32_e32 v17, v17, v3
	v_add_u32_e32 v17, v17, v4
	v_add_u32_e32 v17, v17, v5
	v_add_u32_e32 v17, v17, v6
	v_add_u32_e32 v17, v17, v7
	v_add_u32_e32 v17, v17, v8
	v_add_u32_e32 v17, v17, v9
	v_add_u32_e32 v17, v17, v10
	v_add_u32_e32 v17, v17, v11
	v_add_u32_e32 v17, v17, v12
	v_add_u32_e32 v17, v17, v13
	v_add_u32_e32 v17, v17, v14
	v_add_u32_e32 v17, v17, v15
	v_add_u32_e32 v17, v17, v16
	v_cmp_eq_u32_e32 vcc, s4, v17
	s_mov_b64 s[4:5], -1
	s_cbranch_vccnz .LBB0_865
	s_and_b32 s2, s9, 0xff
	s_cmp_eq_u32 s2, 0
	s_mov_b64 s[2:3], -1
	s_mov_b64 s[6:7], -1
	s_sleep 1
	s_cbranch_scc1 .LBB0_870
	s_and_b64 vcc, exec, s[6:7]
	s_cbranch_vccz .LBB0_865
